# v33 + mlstm_out HM stores staged through unused LDS pad columns into full-line write-through 16B stores
# baseline (speedup 1.0000x reference)
.LBB0_483:
	s_ashr_i32 s6, s68, 3
	s_lshl_b32 s7, s6, 5
	s_addk_i32 s7, 0x4000
	s_lshl_b32 s12, s6, 6
	s_cmpk_lt_i32 s6, 0x200
	s_cselect_b32 s6, s12, s7
	s_cselect_b32 s22, 64, 32
	s_and_b32 s98, s68, 7
	s_lshl_b32 s98, s98, 8
	s_mul_i32 s99, s6, 0x1800
	s_add_i32 s98, s98, s99
	s_addk_i32 s98, 0x800
	s_add_u32 s98, s10, s98
	s_addc_u32 s99, s11, 0
	v_readlane_b32 s100, v253, 48
	v_and_b32_e32 v232, 15, v207
	v_lshrrev_b32_e32 v233, 5, v207
	s_mul_i32 s100, s100, 0x4c00
	v_mul_u32_u24_e32 v232, 0x480, v232
	v_mul_u32_u24_e32 v233, 0x90, v233
	v_add_u32_e32 v232, v232, v233
	v_bfe_u32 v233, v207, 4, 1
	v_lshl_add_u32 v232, v233, 3, v232
	v_add_u32_e32 v232, s100, v232
	v_add_u32_e32 v232, 0x80, v232
	v_mul_u32_u24_e32 v233, 0x90, v207
	v_add_u32_e32 v233, s100, v233
	v_add_u32_e32 v233, 0x80, v233
	v_lshrrev_b32_e32 v164, 3, v207
	v_mul_u32_u24_e32 v164, 0x1800, v164
	v_and_b32_e32 v206, 7, v207
	v_lshl_add_u32 v164, v206, 4, v164
	s_waitcnt vmcnt(0)
	v_add_u32_e32 v2, s6, v207
	v_cmp_gt_u32_e32 vcc, s22, v207
	v_mov_b32_e32 v1, 0xff800000
	v_ashrrev_i32_e32 v3, 31, v2
	s_and_saveexec_b64 s[52:53], vcc
	s_cbranch_execz .LBB0_485
	v_lshlrev_b64 v[8:9], 6, v[2:3]
	v_lshl_add_u64 v[8:9], s[64:65], 0, v[8:9]
	global_load_dword v1, v[8:9], off

.LBB0_489:
	s_add_i32 s69, s69, 1
	s_add_i32 s23, s23, 16
	s_add_u32 s98, s98, 0x18000
	s_addc_u32 s99, s99, 0
	v_lshl_add_u64 v[182:183], v[182:183], 0, s[14:15]
	s_cmp_eq_u32 s23, 64
	v_add_u32_e32 v131, 64, v131
	s_cbranch_scc1 .LBB0_482

.LBB0_497:
	s_waitcnt lgkmcnt(0)
	v_sub_f32_e32 v2, v65, v88
	v_mul_f32_e32 v2, 0x3fb8aa3b, v2
	v_exp_f32_e32 v2, v2
	v_sub_f32_e32 v1, v64, v88
	v_mul_f32_e32 v1, 0x3fb8aa3b, v1
	v_sub_f32_e32 v3, v67, v88
	v_mul_f32_e32 v2, v57, v2
	v_cndmask_b32_e64 v16, 0, v2, s[62:63]
	v_sub_f32_e32 v2, v66, v88
	v_exp_f32_e32 v1, v1
	v_mul_f32_e32 v2, 0x3fb8aa3b, v2
	v_mul_f32_e32 v3, 0x3fb8aa3b, v3
	v_exp_f32_e32 v2, v2
	v_exp_f32_e32 v3, v3
	v_mul_f32_e32 v1, v56, v1
	v_cndmask_b32_e64 v1, 0, v1, s[60:61]
	v_cvt_pk_bf16_f32 v16, v1, v16
	v_pk_mul_f32 v[2:3], v[58:59], v[2:3]
	global_load_dwordx4 v[92:95], v[166:167], off
	global_load_dwordx4 v[88:91], v[168:169], off
	global_load_dwordx4 v[80:83], v[170:171], off
	global_load_dwordx4 v[84:87], v[172:173], off
	global_load_dwordx4 v[72:75], v[174:175], off
	global_load_dwordx4 v[76:79], v[176:177], off
	global_load_dwordx4 v[64:67], v[178:179], off
	global_load_dwordx4 v[56:59], v[180:181], off
	v_cvt_pk_bf16_f32 v1, v2, v3
	v_cndmask_b32_e64 v2, 0, v1, s[58:59]
	v_lshrrev_b32_e32 v1, 16, v1
	v_cndmask_b32_e64 v1, 0, v1, s[56:57]
	v_perm_b32 v17, v1, v2, s85
	v_lshl_add_u64 v[2:3], v[182:183], 0, v[120:121]
	global_load_dwordx2 v[198:199], v[2:3], off offset:-128
	global_load_dwordx2 v[196:197], v[2:3], off offset:-96
	global_load_dwordx2 v[194:195], v[2:3], off offset:-64
	global_load_dwordx2 v[192:193], v[2:3], off offset:-32
	global_load_dwordx2 v[188:189], v[2:3], off
	global_load_dwordx2 v[186:187], v[2:3], off offset:32
	global_load_dwordx2 v[184:185], v[2:3], off offset:64
	s_nop 0
	global_load_dwordx2 v[2:3], v[2:3], off offset:96
	v_mfma_f32_16x16x32_bf16 v[48:51], v[48:51], v[12:15], 0
	v_add_u32_e32 v1, 0x800, v229
	v_mfma_f32_16x16x32_bf16 v[48:51], v[52:55], v[8:11], v[48:51]
	ds_read2_b64 v[52:55], v1 offset0:32 offset1:36
	v_mfma_f32_16x16x32_bf16 v[44:47], v[44:47], v[12:15], 0
	v_mfma_f32_16x16x32_bf16 v[40:43], v[40:43], v[8:11], v[44:47]
	s_nop 4
	v_mul_f32_e64 v50, v190, v50
	v_mul_f32_e64 v51, v190, v51
	v_pk_mul_f32 v[48:49], v[190:191], v[48:49] op_sel_hi:[0,1]
	v_mfma_f32_16x16x32_bf16 v[36:39], v[36:39], v[12:15], 0
	s_waitcnt lgkmcnt(0)
	v_mfma_f32_16x16x32_bf16 v[48:51], v[52:55], v[16:19], v[48:51]
	ds_read2_b64 v[52:55], v1 offset0:40 offset1:44
	v_add_u32_e32 v1, 0x1000, v229
	ds_read2_b64 v[44:47], v1 offset0:64 offset1:68
	v_mfma_f32_16x16x32_bf16 v[28:31], v[28:31], v[12:15], 0
	v_mul_f32_e64 v42, v190, v42
	v_mul_f32_e64 v43, v190, v43
	v_pk_mul_f32 v[40:41], v[190:191], v[40:41] op_sel_hi:[0,1]
	v_mfma_f32_16x16x32_bf16 v[32:35], v[32:35], v[8:11], v[36:39]
	s_waitcnt lgkmcnt(0)
	v_mfma_f32_16x16x32_bf16 v[40:43], v[44:47], v[16:19], v[40:43]
	ds_read2_b64 v[44:47], v1 offset0:72 offset1:76
	v_add_u32_e32 v1, 0x2000, v229
	ds_read2_b64 v[36:39], v230 offset1:4
	v_mfma_f32_16x16x32_bf16 v[24:27], v[24:27], v[8:11], v[28:31]
	s_nop 1
	v_mul_f32_e64 v34, v190, v34
	v_mul_f32_e64 v35, v190, v35
	v_pk_mul_f32 v[32:33], v[190:191], v[32:33] op_sel_hi:[0,1]
	ds_read2_b64 v[28:31], v1 offset0:128 offset1:132
	s_waitcnt lgkmcnt(1)
	v_mfma_f32_16x16x32_bf16 v[32:35], v[36:39], v[16:19], v[32:35]
	v_mul_f32_e64 v26, v190, v26
	v_mul_f32_e64 v27, v190, v27
	v_pk_mul_f32 v[24:25], v[190:191], v[24:25] op_sel_hi:[0,1]
	ds_read2_b64 v[36:39], v230 offset0:8 offset1:12
	s_waitcnt lgkmcnt(0)
	v_mfma_f32_16x16x32_bf16 v[32:35], v[36:39], v[20:23], v[32:35]
	v_mfma_f32_16x16x32_bf16 v[24:27], v[28:31], v[16:19], v[24:27]
	ds_read2_b64 v[28:31], v1 offset0:136 offset1:140
	v_add_u32_e32 v1, 0x2800, v229
	ds_read2_b64 v[36:39], v1 offset0:160 offset1:164
	s_waitcnt lgkmcnt(1)
	v_mfma_f32_16x16x32_bf16 v[24:27], v[28:31], v[20:23], v[24:27]
	s_waitcnt vmcnt(15)
	v_mfma_f32_16x16x32_bf16 v[28:31], v[92:95], v[12:15], 0
	s_waitcnt vmcnt(14)
	v_mfma_f32_16x16x32_bf16 v[28:31], v[88:91], v[8:11], v[28:31]
	v_mfma_f32_16x16x32_bf16 v[40:43], v[44:47], v[20:23], v[40:43]
	v_mfma_f32_16x16x32_bf16 v[48:51], v[52:55], v[20:23], v[48:51]
	s_nop 5
	v_mul_f32_e64 v30, v190, v30
	v_mul_f32_e64 v31, v190, v31
	v_pk_mul_f32 v[28:29], v[190:191], v[28:29] op_sel_hi:[0,1]
	ds_read2_b64 v[52:55], v231 offset1:4
	v_mfma_f32_16x16x32_bf16 v[60:63], v[60:63], v[12:15], 0
	s_waitcnt lgkmcnt(1)
	v_mfma_f32_16x16x32_bf16 v[28:31], v[36:39], v[16:19], v[28:31]
	ds_read2_b64 v[36:39], v1 offset0:168 offset1:172
	v_add_u32_e32 v1, 0x3000, v229
	ds_read2_b64 v[44:47], v1 offset0:192 offset1:196
	s_waitcnt lgkmcnt(1)
	v_mfma_f32_16x16x32_bf16 v[28:31], v[36:39], v[20:23], v[28:31]
	s_waitcnt vmcnt(13)
	v_mfma_f32_16x16x32_bf16 v[36:39], v[80:83], v[12:15], 0
	s_waitcnt vmcnt(12)
	v_mfma_f32_16x16x32_bf16 v[36:39], v[84:87], v[8:11], v[36:39]
	v_mfma_f32_16x16x32_bf16 v[60:63], v[68:71], v[8:11], v[60:63]
	ds_read2_b64 v[68:71], v229 offset1:4
	s_nop 5
	v_pk_mul_f32 v[38:39], v[190:191], v[38:39] op_sel_hi:[0,1]
	v_pk_mul_f32 v[36:37], v[190:191], v[36:37] op_sel_hi:[0,1]
	s_waitcnt lgkmcnt(1)
	s_nop 0
	v_mfma_f32_16x16x32_bf16 v[36:39], v[44:47], v[16:19], v[36:39]
	ds_read2_b64 v[44:47], v1 offset0:200 offset1:204
	v_pk_mul_f32 v[62:63], v[190:191], v[62:63] op_sel_hi:[0,1]
	v_pk_mul_f32 v[60:61], v[190:191], v[60:61] op_sel_hi:[0,1]
	s_waitcnt lgkmcnt(0)
	v_mfma_f32_16x16x32_bf16 v[44:47], v[44:47], v[20:23], v[36:39]
	s_waitcnt vmcnt(11)
	v_mfma_f32_16x16x32_bf16 v[36:39], v[72:75], v[12:15], 0
	s_waitcnt vmcnt(10)
	v_mfma_f32_16x16x32_bf16 v[36:39], v[76:79], v[8:11], v[36:39]
	v_mfma_f32_16x16x32_bf16 v[60:63], v[68:71], v[16:19], v[60:63]
	ds_read2_b64 v[68:71], v229 offset0:8 offset1:12
	s_nop 5
	v_pk_mul_f32 v[38:39], v[190:191], v[38:39] op_sel_hi:[0,1]
	v_pk_mul_f32 v[36:37], v[190:191], v[36:37] op_sel_hi:[0,1]
	s_waitcnt lgkmcnt(0)
	v_mfma_f32_16x16x32_bf16 v[60:63], v[68:71], v[20:23], v[60:63]
	v_mfma_f32_16x16x32_bf16 v[36:39], v[52:55], v[16:19], v[36:39]
	ds_read2_b64 v[52:55], v231 offset0:8 offset1:12
	s_waitcnt lgkmcnt(0)
	v_mfma_f32_16x16x32_bf16 v[36:39], v[52:55], v[20:23], v[36:39]
	s_waitcnt vmcnt(9)
	v_cndmask_b32_e64 v55, 0, v67, s[38:39]
	v_cndmask_b32_e64 v54, 0, v66, s[38:39]
	v_cndmask_b32_e64 v53, 0, v65, s[38:39]
	v_cndmask_b32_e64 v52, 0, v64, s[38:39]
	s_nop 1
	v_mfma_f32_16x16x32_bf16 v[12:15], v[52:55], v[12:15], 0
	s_waitcnt vmcnt(8)
	v_cndmask_b32_e64 v55, 0, v59, s[38:39]
	v_cndmask_b32_e64 v54, 0, v58, s[38:39]
	v_cndmask_b32_e64 v53, 0, v57, s[38:39]
	v_cndmask_b32_e64 v52, 0, v56, s[38:39]
	s_nop 1
	v_mfma_f32_16x16x32_bf16 v[8:11], v[52:55], v[8:11], v[12:15]
	s_nop 7
	v_pk_mul_f32 v[10:11], v[190:191], v[10:11] op_sel_hi:[0,1]
	v_pk_mul_f32 v[8:9], v[190:191], v[8:9] op_sel_hi:[0,1]
	s_nop 1
	v_mfma_f32_16x16x32_bf16 v[8:11], v[4:7], v[16:19], v[8:11]
	v_mfma_f32_16x16x32_bf16 v[8:11], v[4:7], v[20:23], v[8:11]
	s_nop 7
	ds_bpermute_b32 v1, v211, v8
	v_max_f32_e32 v8, v135, v135
	s_waitcnt lgkmcnt(0)
	v_max_f32_e64 v1, |v1|, |v1|
	v_max_f32_e32 v1, v1, v8
	v_div_scale_f32 v8, s[6:7], v1, v1, 1.0
	v_rcp_f32_e32 v9, v8
	s_nop 0
	v_fma_f32 v10, -v8, v9, 1.0
	v_fmac_f32_e32 v9, v10, v9
	v_div_scale_f32 v10, vcc, 1.0, v1, 1.0
	v_mul_f32_e32 v11, v10, v9
	v_fma_f32 v12, -v8, v11, v10
	v_fmac_f32_e32 v11, v12, v9
	v_fma_f32 v8, -v8, v11, v10
	v_div_fmas_f32 v8, v8, v9, v11
	v_div_fixup_f32 v14, v8, v1, 1.0
	v_pk_mul_f32 v[18:19], v[62:63], v[14:15] op_sel_hi:[1,0]
	v_pk_mul_f32 v[52:53], v[60:61], v[14:15] op_sel_hi:[1,0]
	v_mul_f32_e32 v8, v19, v19
	v_mul_f32_e32 v1, v53, v53
	v_fmac_f32_e32 v1, v52, v52
	v_fmac_f32_e32 v8, v18, v18
	v_pk_mul_f32 v[50:51], v[50:51], v[14:15] op_sel_hi:[1,0]
	v_pk_mul_f32 v[48:49], v[48:49], v[14:15] op_sel_hi:[1,0]
	v_add_f32_e32 v1, v1, v8
	v_mul_f32_e32 v8, v49, v49
	v_mul_f32_e32 v9, v51, v51
	v_fmac_f32_e32 v8, v48, v48
	v_fmac_f32_e32 v9, v50, v50
	v_add_f32_e32 v8, v8, v9
	v_pk_mul_f32 v[42:43], v[42:43], v[14:15] op_sel_hi:[1,0]
	v_pk_mul_f32 v[40:41], v[40:41], v[14:15] op_sel_hi:[1,0]
	v_add_f32_e32 v1, v1, v8
	v_mul_f32_e32 v8, v41, v41
	v_mul_f32_e32 v9, v43, v43
	v_fmac_f32_e32 v8, v40, v40
	v_fmac_f32_e32 v9, v42, v42
	v_add_f32_e32 v8, v8, v9
	v_pk_mul_f32 v[34:35], v[34:35], v[14:15] op_sel_hi:[1,0]
	v_pk_mul_f32 v[32:33], v[32:33], v[14:15] op_sel_hi:[1,0]
	v_add_f32_e32 v1, v8, v1
	v_mul_f32_e32 v8, v33, v33
	v_mul_f32_e32 v9, v35, v35
	v_fmac_f32_e32 v8, v32, v32
	v_fmac_f32_e32 v9, v34, v34
	v_add_f32_e32 v8, v8, v9
	v_pk_mul_f32 v[22:23], v[26:27], v[14:15] op_sel_hi:[1,0]
	v_pk_mul_f32 v[26:27], v[24:25], v[14:15] op_sel_hi:[1,0]
	v_add_f32_e32 v1, v8, v1
	v_mul_f32_e32 v8, v27, v27
	v_mul_f32_e32 v9, v23, v23
	v_fmac_f32_e32 v8, v26, v26
	v_fmac_f32_e32 v9, v22, v22
	v_add_f32_e32 v8, v8, v9
	v_pk_mul_f32 v[20:21], v[30:31], v[14:15] op_sel_hi:[1,0]
	v_pk_mul_f32 v[24:25], v[28:29], v[14:15] op_sel_hi:[1,0]
	v_add_f32_e32 v1, v8, v1
	v_mul_f32_e32 v8, v25, v25
	v_mul_f32_e32 v9, v21, v21
	v_fmac_f32_e32 v8, v24, v24
	v_fmac_f32_e32 v9, v20, v20
	v_add_f32_e32 v8, v8, v9
	v_add_f32_e32 v1, v8, v1
	v_pk_mul_f32 v[8:9], v[46:47], v[14:15] op_sel_hi:[1,0]
	v_pk_mul_f32 v[10:11], v[44:45], v[14:15] op_sel_hi:[1,0]
	v_mul_f32_e32 v13, v9, v9
	v_mul_f32_e32 v12, v11, v11
	v_fmac_f32_e32 v12, v10, v10
	v_fmac_f32_e32 v13, v8, v8
	v_add_f32_e32 v12, v12, v13
	v_add_f32_e32 v1, v12, v1
	v_pk_mul_f32 v[12:13], v[38:39], v[14:15] op_sel_hi:[1,0]
	v_pk_mul_f32 v[14:15], v[36:37], v[14:15] op_sel_hi:[1,0]
	v_mul_f32_e32 v17, v13, v13
	v_mul_f32_e32 v16, v15, v15
	v_fmac_f32_e32 v16, v14, v14
	v_fmac_f32_e32 v17, v12, v12
	v_add_f32_e32 v16, v16, v17
	v_add_f32_e32 v1, v16, v1
	ds_bpermute_b32 v16, v212, v1
	v_cmp_gt_u32_e32 vcc, s22, v133
	s_waitcnt lgkmcnt(0)
	v_add_f32_e32 v1, v1, v16
	ds_bpermute_b32 v16, v213, v1
	s_and_saveexec_b64 s[58:59], vcc
	s_cbranch_execz .LBB0_488
	s_waitcnt lgkmcnt(0)
	v_add_f32_e32 v1, v1, v16
	v_mov_b32_e32 v16, 0x358637bd
	v_fmamk_f32 v1, v1, 0x3c000000, v16
	s_mov_b32 s6, 0xf800000
	v_cmp_gt_f32_e32 vcc, s6, v1
	v_mul_f32_e32 v16, 0x4f800000, v1
	s_waitcnt vmcnt(7)
	v_lshlrev_b32_e32 v46, 16, v199
	v_cndmask_b32_e32 v1, v1, v16, vcc
	v_sqrt_f32_e32 v16, v1
	v_and_b32_e32 v47, 0xffff0000, v199
	v_mov_b32_e32 v135, v0
	v_mov_b32_e32 v137, v0
	v_add_u32_e32 v17, -1, v16
	v_fma_f32 v28, -v17, v16, v1
	v_cmp_ge_f32_e64 s[56:57], 0, v28
	v_add_u32_e32 v28, 1, v16
	v_mov_b32_e32 v139, v0
	v_cndmask_b32_e64 v17, v16, v17, s[56:57]
	v_fma_f32 v16, -v28, v16, v1
	v_cmp_lt_f32_e64 s[56:57], 0, v16
	s_nop 1
	v_cndmask_b32_e64 v16, v17, v28, s[56:57]
	v_mul_f32_e32 v17, 0x37800000, v16
	v_cndmask_b32_e32 v16, v16, v17, vcc
	v_mov_b32_e32 v17, 0x260
	v_cmp_class_f32_e32 vcc, v1, v17
	s_nop 1
	v_cndmask_b32_e32 v1, v16, v1, vcc
	v_div_scale_f32 v16, s[6:7], v1, v1, 1.0
	v_rcp_f32_e32 v17, v16
	s_nop 0
	v_fma_f32 v28, -v16, v17, 1.0
	v_fmac_f32_e32 v17, v28, v17
	v_div_scale_f32 v28, vcc, 1.0, v1, 1.0
	v_mul_f32_e32 v29, v28, v17
	v_fma_f32 v30, -v16, v29, v28
	v_fmac_f32_e32 v29, v30, v17
	v_fma_f32 v16, -v16, v29, v28
	v_div_fmas_f32 v16, v16, v17, v29
	v_div_fixup_f32 v16, v16, v1, 1.0
	v_add_u32_e32 v1, s23, v129
	v_and_b32_e32 v1, 0x7fffffff, v1
	v_mov_b64_e32 v[28:29], s[66:67]
	v_mad_u64_u32 v[36:37], s[6:7], v1, s84, v[28:29]
	v_lshlrev_b32_e32 v1, 16, v198
	v_mul_f32_e32 v1, 0xbfb8aa3b, v1
	v_exp_f32_e32 v1, v1
	v_and_b32_e32 v17, 0xffff0000, v198
	ds_read_b128 v[28:31], v210 offset:18688
	v_pk_mul_f32 v[44:45], v[52:53], v[16:17] op_sel_hi:[1,0]
	v_add_f32_e32 v1, 1.0, v1
	v_rcp_f32_e32 v38, v1
	v_mul_f32_e32 v1, 0xbfb8aa3b, v17
	v_exp_f32_e32 v1, v1
	s_waitcnt lgkmcnt(0)
	v_pk_mul_f32 v[28:29], v[44:45], v[28:29]
	v_pk_mul_f32 v[18:19], v[18:19], v[16:17] op_sel_hi:[1,0]
	s_waitcnt vmcnt(6)
	v_and_b32_e32 v17, 0xffff0000, v196
	v_add_f32_e32 v1, 1.0, v1
	v_rcp_f32_e32 v39, v1
	v_mul_f32_e32 v1, 0xbfb8aa3b, v46
	v_exp_f32_e32 v1, v1
	v_pk_mul_f32 v[18:19], v[18:19], v[30:31]
	v_pk_mul_f32 v[28:29], v[38:39], v[28:29]
	v_lshlrev_b32_e32 v46, 16, v197
	v_add_f32_e32 v1, 1.0, v1
	v_rcp_f32_e32 v38, v1
	v_mul_f32_e32 v1, 0xbfb8aa3b, v47
	v_exp_f32_e32 v1, v1
	v_cvt_pk_bf16_f32 v28, v28, v29
	v_pk_mul_f32 v[44:45], v[48:49], v[16:17] op_sel_hi:[1,0]
	v_and_b32_e32 v47, 0xffff0000, v197
	v_add_f32_e32 v1, 1.0, v1
	v_rcp_f32_e32 v39, v1
	v_lshlrev_b32_e32 v1, 16, v196
	v_mul_f32_e32 v1, 0xbfb8aa3b, v1
	v_exp_f32_e32 v1, v1
	v_pk_mul_f32 v[18:19], v[38:39], v[18:19]
	v_add_f32_e32 v1, 1.0, v1
	v_rcp_f32_e32 v38, v1
	v_mul_f32_e32 v1, 0xbfb8aa3b, v17
	v_exp_f32_e32 v1, v1
	v_cvt_pk_bf16_f32 v29, v18, v19
	v_lshlrev_b32_e32 v18, 1, v96
	v_mov_b32_e32 v19, v0
	v_lshl_add_u64 v[18:19], v[36:37], 0, v[18:19]
	v_add_f32_e32 v1, 1.0, v1
	ds_write_b64 v232, v[28:29]
	ds_read_b128 v[28:31], v216 offset:18688
	v_rcp_f32_e32 v39, v1
	v_mul_f32_e32 v1, 0xbfb8aa3b, v46
	v_exp_f32_e32 v1, v1
	s_waitcnt lgkmcnt(0)
	v_pk_mul_f32 v[28:29], v[44:45], v[28:29]
	s_nop 0
	v_pk_mul_f32 v[28:29], v[38:39], v[28:29]
	v_add_f32_e32 v1, 1.0, v1
	v_rcp_f32_e32 v38, v1
	v_mul_f32_e32 v1, 0xbfb8aa3b, v47
	v_exp_f32_e32 v1, v1
	v_pk_mul_f32 v[44:45], v[50:51], v[16:17] op_sel_hi:[1,0]
	s_waitcnt vmcnt(5)
	v_and_b32_e32 v17, 0xffff0000, v194
	v_pk_mul_f32 v[30:31], v[44:45], v[30:31]
	v_add_f32_e32 v1, 1.0, v1
	v_rcp_f32_e32 v39, v1
	v_lshlrev_b32_e32 v1, 16, v194
	v_mul_f32_e32 v1, 0xbfb8aa3b, v1
	v_exp_f32_e32 v1, v1
	v_pk_mul_f32 v[30:31], v[38:39], v[30:31]
	v_cvt_pk_bf16_f32 v28, v28, v29
	v_cvt_pk_bf16_f32 v29, v30, v31
	v_add_f32_e32 v1, 1.0, v1
	v_rcp_f32_e32 v38, v1
	v_mul_f32_e32 v1, 0xbfb8aa3b, v17
	v_exp_f32_e32 v1, v1
	v_lshl_add_u64 v[30:31], v[36:37], 0, v[134:135]
	v_lshlrev_b32_e32 v44, 16, v195
	ds_write_b64 v232, v[28:29] offset:288
	v_add_f32_e32 v1, 1.0, v1
	ds_read_b128 v[28:31], v217 offset:18688
	v_rcp_f32_e32 v39, v1
	v_mul_f32_e32 v1, 0xbfb8aa3b, v44
	v_exp_f32_e32 v1, v1
	v_pk_mul_f32 v[40:41], v[40:41], v[16:17] op_sel_hi:[1,0]
	v_and_b32_e32 v45, 0xffff0000, v195
	s_waitcnt lgkmcnt(0)
	v_pk_mul_f32 v[28:29], v[40:41], v[28:29]
	v_add_f32_e32 v1, 1.0, v1
	v_pk_mul_f32 v[28:29], v[38:39], v[28:29]
	v_rcp_f32_e32 v38, v1
	v_mul_f32_e32 v1, 0xbfb8aa3b, v45
	v_exp_f32_e32 v1, v1
	v_pk_mul_f32 v[40:41], v[42:43], v[16:17] op_sel_hi:[1,0]
	s_waitcnt vmcnt(4)
	v_and_b32_e32 v17, 0xffff0000, v192
	v_pk_mul_f32 v[30:31], v[40:41], v[30:31]
	v_add_f32_e32 v1, 1.0, v1
	v_rcp_f32_e32 v39, v1
	v_lshlrev_b32_e32 v1, 16, v192
	v_mul_f32_e32 v1, 0xbfb8aa3b, v1
	v_exp_f32_e32 v1, v1
	v_pk_mul_f32 v[30:31], v[38:39], v[30:31]
	v_lshlrev_b32_e32 v40, 16, v193
	v_cvt_pk_bf16_f32 v28, v28, v29
	v_add_f32_e32 v1, 1.0, v1
	v_rcp_f32_e32 v38, v1
	v_mul_f32_e32 v1, 0xbfb8aa3b, v17
	v_exp_f32_e32 v1, v1
	v_cvt_pk_bf16_f32 v29, v30, v31
	v_lshl_add_u64 v[30:31], v[36:37], 0, v[136:137]
	ds_write_b64 v232, v[28:29] offset:576
	v_add_f32_e32 v1, 1.0, v1
	v_rcp_f32_e32 v39, v1
	v_mul_f32_e32 v1, 0xbfb8aa3b, v40
	ds_read_b128 v[28:31], v218 offset:18688
	v_exp_f32_e32 v1, v1
	v_and_b32_e32 v41, 0xffff0000, v193
	v_pk_mul_f32 v[32:33], v[32:33], v[16:17] op_sel_hi:[1,0]
	v_pk_mul_f32 v[34:35], v[34:35], v[16:17] op_sel_hi:[1,0]
	v_add_f32_e32 v1, 1.0, v1
	s_waitcnt lgkmcnt(0)
	v_pk_mul_f32 v[28:29], v[32:33], v[28:29]
	v_rcp_f32_e32 v32, v1
	v_mul_f32_e32 v1, 0xbfb8aa3b, v41
	v_exp_f32_e32 v1, v1
	v_pk_mul_f32 v[30:31], v[34:35], v[30:31]
	s_waitcnt vmcnt(3)
	v_and_b32_e32 v17, 0xffff0000, v188
	v_pk_mul_f32 v[28:29], v[38:39], v[28:29]
	v_add_f32_e32 v1, 1.0, v1
	v_rcp_f32_e32 v33, v1
	v_lshlrev_b32_e32 v1, 16, v188
	v_mul_f32_e32 v1, 0xbfb8aa3b, v1
	v_exp_f32_e32 v1, v1
	v_pk_mul_f32 v[30:31], v[32:33], v[30:31]
	v_lshlrev_b32_e32 v34, 16, v189
	v_cvt_pk_bf16_f32 v28, v28, v29
	v_add_f32_e32 v1, 1.0, v1
	v_rcp_f32_e32 v32, v1
	v_mul_f32_e32 v1, 0xbfb8aa3b, v17
	v_exp_f32_e32 v1, v1
	v_cvt_pk_bf16_f32 v29, v30, v31
	v_lshl_add_u64 v[30:31], v[36:37], 0, v[138:139]
	ds_write_b64 v232, v[28:29] offset:864
	s_waitcnt lgkmcnt(0)
	ds_read_b128 v[242:245], v233
	s_add_u32 s100, s98, 0xc000
	s_addc_u32 s101, s99, 0
	s_waitcnt lgkmcnt(0)
	global_store_dwordx4 v164, v[242:245], s[98:99] sc1
	s_nop 0
	ds_read_b128 v[242:245], v233 offset:9216
	s_waitcnt lgkmcnt(0)
	global_store_dwordx4 v164, v[242:245], s[100:101] sc1
	v_add_f32_e32 v1, 1.0, v1
	v_rcp_f32_e32 v33, v1
	v_mul_f32_e32 v1, 0xbfb8aa3b, v34
	ds_read_b128 v[28:31], v210 offset:18944
	v_exp_f32_e32 v1, v1
	v_and_b32_e32 v35, 0xffff0000, v189
	v_pk_mul_f32 v[26:27], v[26:27], v[16:17] op_sel_hi:[1,0]
	v_pk_mul_f32 v[22:23], v[22:23], v[16:17] op_sel_hi:[1,0]
	v_add_f32_e32 v1, 1.0, v1
	s_waitcnt lgkmcnt(0)
	v_pk_mul_f32 v[26:27], v[26:27], v[28:29]
	v_rcp_f32_e32 v28, v1
	v_mul_f32_e32 v1, 0xbfb8aa3b, v35
	v_exp_f32_e32 v1, v1
	v_pk_mul_f32 v[22:23], v[22:23], v[30:31]
	v_pk_mul_f32 v[26:27], v[32:33], v[26:27]
	s_waitcnt vmcnt(4)
	v_and_b32_e32 v17, 0xffff0000, v186
	v_add_f32_e32 v1, 1.0, v1
	v_rcp_f32_e32 v29, v1
	v_lshlrev_b32_e32 v1, 16, v186
	v_mul_f32_e32 v1, 0xbfb8aa3b, v1
	v_exp_f32_e32 v1, v1
	v_pk_mul_f32 v[22:23], v[28:29], v[22:23]
	v_cvt_pk_bf16_f32 v26, v26, v27
	v_cvt_pk_bf16_f32 v27, v22, v23
	v_add_f32_e32 v1, 1.0, v1
	v_rcp_f32_e32 v22, v1
	v_mul_f32_e32 v1, 0xbfb8aa3b, v17
	v_exp_f32_e32 v1, v1
	v_lshlrev_b32_e32 v30, 16, v187
	ds_write_b64 v232, v[26:27]
	ds_read_b128 v[26:29], v210 offset:19008
	v_add_f32_e32 v1, 1.0, v1
	v_rcp_f32_e32 v23, v1
	v_mul_f32_e32 v1, 0xbfb8aa3b, v30
	v_exp_f32_e32 v1, v1
	v_pk_mul_f32 v[24:25], v[24:25], v[16:17] op_sel_hi:[1,0]
	v_and_b32_e32 v31, 0xffff0000, v187
	s_waitcnt lgkmcnt(0)
	v_pk_mul_f32 v[24:25], v[24:25], v[26:27]
	v_add_f32_e32 v1, 1.0, v1
	v_pk_mul_f32 v[22:23], v[22:23], v[24:25]
	v_rcp_f32_e32 v24, v1
	v_mul_f32_e32 v1, 0xbfb8aa3b, v31
	v_exp_f32_e32 v1, v1
	v_pk_mul_f32 v[20:21], v[20:21], v[16:17] op_sel_hi:[1,0]
	s_waitcnt vmcnt(3)
	v_and_b32_e32 v17, 0xffff0000, v184
	v_pk_mul_f32 v[20:21], v[20:21], v[28:29]
	v_add_f32_e32 v1, 1.0, v1
	v_rcp_f32_e32 v25, v1
	v_lshlrev_b32_e32 v1, 16, v184
	v_mul_f32_e32 v1, 0xbfb8aa3b, v1
	v_exp_f32_e32 v1, v1
	v_pk_mul_f32 v[20:21], v[24:25], v[20:21]
	v_lshlrev_b32_e32 v26, 16, v185
	v_cvt_pk_bf16_f32 v22, v22, v23
	v_add_f32_e32 v1, 1.0, v1
	v_rcp_f32_e32 v24, v1
	v_mul_f32_e32 v1, 0xbfb8aa3b, v17
	v_exp_f32_e32 v1, v1
	v_cvt_pk_bf16_f32 v23, v20, v21
	ds_write_b64 v232, v[22:23] offset:288
	ds_read_b128 v[20:23], v210 offset:19072
	v_add_f32_e32 v1, 1.0, v1
	v_rcp_f32_e32 v25, v1
	v_mul_f32_e32 v1, 0xbfb8aa3b, v26
	v_exp_f32_e32 v1, v1
	v_and_b32_e32 v27, 0xffff0000, v185
	v_pk_mul_f32 v[10:11], v[10:11], v[16:17] op_sel_hi:[1,0]
	v_pk_mul_f32 v[8:9], v[8:9], v[16:17] op_sel_hi:[1,0]
	v_add_f32_e32 v1, 1.0, v1
	s_waitcnt lgkmcnt(0)
	v_pk_mul_f32 v[10:11], v[10:11], v[20:21]
	v_rcp_f32_e32 v20, v1
	v_mul_f32_e32 v1, 0xbfb8aa3b, v27
	v_exp_f32_e32 v1, v1
	s_waitcnt vmcnt(2)
	v_and_b32_e32 v17, 0xffff0000, v2
	v_pk_mul_f32 v[8:9], v[8:9], v[22:23]
	v_pk_mul_f32 v[10:11], v[24:25], v[10:11]
	v_add_f32_e32 v1, 1.0, v1
	v_rcp_f32_e32 v21, v1
	v_lshlrev_b32_e32 v1, 16, v2
	v_mul_f32_e32 v1, 0xbfb8aa3b, v1
	v_exp_f32_e32 v1, v1
	v_pk_mul_f32 v[8:9], v[20:21], v[8:9]
	v_cvt_pk_bf16_f32 v10, v10, v11
	v_cvt_pk_bf16_f32 v11, v8, v9
	v_add_f32_e32 v1, 1.0, v1
	v_rcp_f32_e32 v2, v1
	v_mul_f32_e32 v1, 0xbfb8aa3b, v17
	v_exp_f32_e32 v1, v1
	v_lshlrev_b32_e32 v20, 16, v3
	ds_write_b64 v232, v[10:11] offset:576
	ds_read_b128 v[8:11], v210 offset:19136
	v_add_f32_e32 v1, 1.0, v1
	v_and_b32_e32 v21, 0xffff0000, v3
	v_rcp_f32_e32 v3, v1
	v_mul_f32_e32 v1, 0xbfb8aa3b, v20
	v_exp_f32_e32 v1, v1
	v_pk_mul_f32 v[14:15], v[14:15], v[16:17] op_sel_hi:[1,0]
	v_pk_mul_f32 v[12:13], v[12:13], v[16:17] op_sel_hi:[1,0]
	s_waitcnt lgkmcnt(0)
	v_pk_mul_f32 v[8:9], v[14:15], v[8:9]
	v_add_f32_e32 v1, 1.0, v1
	v_pk_mul_f32 v[2:3], v[2:3], v[8:9]
	v_rcp_f32_e32 v8, v1
	v_mul_f32_e32 v1, 0xbfb8aa3b, v21
	v_exp_f32_e32 v1, v1
	v_pk_mul_f32 v[10:11], v[12:13], v[10:11]
	v_cvt_pk_bf16_f32 v2, v2, v3
	v_add_f32_e32 v1, 1.0, v1
	v_rcp_f32_e32 v9, v1
	s_nop 0
	v_pk_mul_f32 v[8:9], v[8:9], v[10:11]
	s_nop 0
	v_cvt_pk_bf16_f32 v3, v8, v9
	ds_write_b64 v232, v[2:3] offset:864
	s_waitcnt lgkmcnt(0)
	ds_read_b128 v[242:245], v233
	s_add_u32 s100, s98, 0xc000
	s_addc_u32 s101, s99, 0
	s_waitcnt lgkmcnt(0)
	global_store_dwordx4 v164, v[242:245], s[98:99] offset:128 sc1
	s_nop 0
	ds_read_b128 v[242:245], v233 offset:9216
	s_waitcnt lgkmcnt(0)
	global_store_dwordx4 v164, v[242:245], s[100:101] offset:128 sc1
	s_branch .LBB0_488
